# kn / v^T GEMMs and GDN pre-phase: unit-to-workgroup assignment rotated per phase so leftover units fall on different workgroups
# speedup vs baseline: 1.0651x; 1.0176x over previous
; #define PG8_LAS __attribute__((address_space(3)))
;     __device__ bool next(int i, Unit& u) const { return i < cnt && s.next(i, u); }
;     __device__ bool next(int i, Unit& u) const { const int q = i * s.G + s.c; if (q >= total) return false; if (!s.mapL((long)base * s.G + q / KS, u)) return false; u.koff = (size_t)(q % KS) * kbytes; u.aux = q; return true; }
;     __host__ __device__ bool mapL(long L, Unit& u) const {
;         if (L >= nwg) return false;
;         int wgid = (int)L; { const int q = nwg / NXCD, r = nwg % NXCD, xcd = wgid % NXCD, off = wgid / NXCD; wgid = (xcd < r ? xcd * (q + 1) : r * (q + 1) + (xcd - r) * q) + off; }
;         const int nig = WGM * nN, gid = wgid / nig, fm = gid * WGM, gsz = (nM - fm) < WGM ? (nM - fm) : WGM;
;         u.pm = fm + ((wgid % nig) % gsz); u.pn = (wgid % nig) / gsz; u.koff = 0; u.aux = 0; return true;
;     }
;     __host__ __device__ bool next(int i, Unit& u) const { return mapL((long)i * G + c, u); }
; template <class Epi> DI void pgemm(unsigned char* lds, const bf16_t* A, int lda, const bf16_t* Bt, int ldb, int Mg, int Ng, int K, const Epi& E) {
;     pg8::Gemm g{A, Bt, Mg, Ng, K, lda, ldb}; pg8::StaticOrder S; S.init(Mg, Ng, (int)gridDim.x, (int)blockIdx.x);
;     pg8::gemm_phase<Epi, pg8::StaticOrder, true, true>((PG8_LAS unsigned char*)lds, g, S, E);
;     __syncthreads();
.LBB0_1088:
	s_add_i32 s99, s3, 216
	s_and_b32 s99, s99, 0xff
	s_add_u32 s2, s34, 0x47cbb00
	s_addc_u32 s15, s35, 0
	s_add_u32 s60, s34, 0x1619a800
	s_addc_u32 s61, s35, 0
	v_mov_b32_e32 v0, v212
	v_mov_b32_e32 v8, v212
	s_cmpk_lt_i32 s99, 0x112
	s_waitcnt vmcnt(0)
	s_barrier
	s_cselect_b64 s[40:41], -1, 0
	s_cmpk_gt_i32 s99, 0x111
	v_readfirstlane_b32 s4, v8
	s_cbranch_scc1 .LBB0_1114
	s_ashr_i32 s16, s99, 31
	s_lshr_b32 s0, s16, 29
	s_add_i32 s5, s99, s0
	s_and_b32 s0, s5, -8
	s_sub_i32 s9, s99, s0
	s_cmp_gt_i32 s9, 1
	s_cbranch_scc0 .LBB0_1091
	s_mul_i32 s0, s9, 34
	s_add_i32 s8, s0, 2
	s_cbranch_execz .LBB0_1092
	s_branch .LBB0_1093

;     __device__ bool next(int i, Unit& u) const { return i < cnt && s.next(i, u); }
;     __device__ bool next(int i, Unit& u) const { const int q = i * s.G + s.c; if (q >= total) return false; if (!s.mapL((long)base * s.G + q / KS, u)) return false; u.koff = (size_t)(q % KS) * kbytes; u.aux = q; return true; }
;     __host__ __device__ bool mapL(long L, Unit& u) const {
;         if (L >= nwg) return false;
;         int wgid = (int)L; { const int q = nwg / NXCD, r = nwg % NXCD, xcd = wgid % NXCD, off = wgid / NXCD; wgid = (xcd < r ? xcd * (q + 1) : r * (q + 1) + (xcd - r) * q) + off; }
;         const int nig = WGM * nN, gid = wgid / nig, fm = gid * WGM, gsz = (nM - fm) < WGM ? (nM - fm) : WGM;
;         u.pm = fm + ((wgid % nig) % gsz); u.pn = (wgid % nig) / gsz; u.koff = 0; u.aux = 0; return true;
;     }
;     __host__ __device__ bool next(int i, Unit& u) const { return mapL((long)i * G + c, u); }
.LBB0_1098:
	s_add_i32 s77, s77, 1
	v_readlane_b32 s0, v246, 2
	s_mul_i32 s0, s77, s0
	s_mul_hi_u32 s1, s77, s74
	s_add_i32 s1, s1, s0
	s_mul_i32 s0, s77, s74
	s_add_u32 s4, s0, s99
	s_addc_u32 s5, s1, s16
	v_cmp_gt_i64_e32 vcc, s[4:5], v[140:141]
	v_cmp_lt_i64_e64 s[0:1], s[4:5], v[138:139]
	s_cbranch_vccnz .LBB0_1104
	s_ashr_i32 s5, s4, 31
	s_lshr_b32 s5, s5, 29
	s_add_i32 s20, s4, s5
	s_and_b32 s5, s20, -8
	s_sub_i32 s21, s4, s5
	s_cmp_gt_i32 s21, 1
	s_mov_b64 s[4:5], -1
	s_cbranch_scc0 .LBB0_1101
	s_mul_i32 s4, s21, 34
	s_add_i32 s26, s4, 2
	s_mov_b64 s[4:5], 0

;     __host__ __device__ bool mapL(long L, Unit& u) const {
;         if (L >= nwg) return false;
;         int wgid = (int)L; { const int q = nwg / NXCD, r = nwg % NXCD, xcd = wgid % NXCD, off = wgid / NXCD; wgid = (xcd < r ? xcd * (q + 1) : r * (q + 1) + (xcd - r) * q) + off; }
;         const int nig = WGM * nN, gid = wgid / nig, fm = gid * WGM, gsz = (nM - fm) < WGM ? (nM - fm) : WGM;
;         u.pm = fm + ((wgid % nig) % gsz); u.pn = (wgid % nig) / gsz; u.koff = 0; u.aux = 0; return true;
;     }
; DI void run_phase(const Prm& p, int ph, unsigned char* lds, int tid, int wid, int lane) {
;     ...
;     case 16: pgemm(lds, (const bf16_t*)(ws + W_WVT), 256, HP + C_CKV, NPJ, 512, M, 256, PEpiBf{(bf16_t*)(ws + W_VT), M, 1.f, nullptr}); break;
.LBB0_1114:
	s_add_i32 s99, s3, 184
	s_and_b32 s99, s99, 0xff
	s_add_u32 s0, s34, 0x183da800
	v_mov_b32_e32 v0, v212
	s_addc_u32 s1, s35, 0
	v_mov_b32_e32 v8, v212
	s_waitcnt vmcnt(0)
	s_barrier
	v_writelane_b32 v246, s0, 14
	s_andn2_b64 vcc, exec, s[40:41]
	v_readfirstlane_b32 s4, v8
	v_writelane_b32 v246, s1, 15
	s_cbranch_vccnz .LBB0_1140
	s_ashr_i32 s16, s99, 31
	s_lshr_b32 s0, s16, 29
	s_add_i32 s5, s99, s0
	s_and_b32 s0, s5, -8
	s_sub_i32 s7, s99, s0
	s_cmp_gt_i32 s7, 1
	s_cbranch_scc0 .LBB0_1117
	s_mul_i32 s0, s7, 34
	s_add_i32 s6, s0, 2
	s_cbranch_execz .LBB0_1118
	s_branch .LBB0_1119

;     __device__ bool next(int i, Unit& u) const { return i < cnt && s.next(i, u); }
;     __device__ bool next(int i, Unit& u) const { const int q = i * s.G + s.c; if (q >= total) return false; if (!s.mapL((long)base * s.G + q / KS, u)) return false; u.koff = (size_t)(q % KS) * kbytes; u.aux = q; return true; }
;     __host__ __device__ bool mapL(long L, Unit& u) const {
;         if (L >= nwg) return false;
;         int wgid = (int)L; { const int q = nwg / NXCD, r = nwg % NXCD, xcd = wgid % NXCD, off = wgid / NXCD; wgid = (xcd < r ? xcd * (q + 1) : r * (q + 1) + (xcd - r) * q) + off; }
;         const int nig = WGM * nN, gid = wgid / nig, fm = gid * WGM, gsz = (nM - fm) < WGM ? (nM - fm) : WGM;
;         u.pm = fm + ((wgid % nig) % gsz); u.pn = (wgid % nig) / gsz; u.koff = 0; u.aux = 0; return true;
;     }
;     __host__ __device__ bool next(int i, Unit& u) const { return mapL((long)i * G + c, u); }
.LBB0_1124:
	s_add_i32 s77, s77, 1
	v_readlane_b32 s0, v246, 2
	s_mul_i32 s0, s77, s0
	s_mul_hi_u32 s1, s77, s48
	s_add_i32 s1, s1, s0
	s_mul_i32 s0, s77, s48
	s_add_u32 s4, s0, s99
	s_addc_u32 s5, s1, s16
	v_cmp_gt_i64_e32 vcc, s[4:5], v[140:141]
	v_cmp_lt_i64_e64 s[0:1], s[4:5], v[138:139]
	s_cbranch_vccnz .LBB0_1130
	s_ashr_i32 s5, s4, 31
	s_lshr_b32 s5, s5, 29
	s_add_i32 s24, s4, s5
	s_and_b32 s5, s24, -8
	s_sub_i32 s25, s4, s5
	s_cmp_gt_i32 s25, 1
	s_mov_b64 s[4:5], -1
	s_cbranch_scc0 .LBB0_1127
	s_mul_i32 s4, s25, 34
	s_add_i32 s44, s4, 2
	s_mov_b64 s[4:5], 0

; DI void gdn_unit_decode(int u, int& kind, int& b, int& c, int& h) { if (u < 2064) { kind = 0; b = u / 516; const int r = u % 516; c = r >> 2; h = r & 3; } else { kind = 1; b = (u - 2064) >> 2; c = 0; h = u & 3; } }
; DI void gdn_pre_unit(const Prm& p, unsigned char* lds0, int u, int tid, int wid, int lane) {
;     int loff = 0; asm volatile("" : "+s"(loff)); unsigned char* lds = lds0 + loff;
;     bf16_t* qL = (bf16_t*)(lds + GP_Q); bf16_t* kL = (bf16_t*)(lds + GP_K); bf16_t* kegL = (bf16_t*)(lds + GP_KEG); bf16_t* vtL = (bf16_t*)(lds + GP_VT); bf16_t* kdL = (bf16_t*)(lds + GP_KD);
;     bf16_t* tbL = (bf16_t*)(lds + GP_TB); float* AL = (float*)(lds + GP_A); float* gL = (float*)(lds + GP_G);
;     unsigned char* ex = p.ws + W_EX + (size_t)u * EXB;
;     int kind, b, c, h; gdn_unit_decode(u, kind, b, c, h);
;     const int lr = lane & 31, hi = lane >> 5;
;     __syncthreads();
;     if (wid == 0) { float gc, beta; gdn_gates(p, kind, b, c, h, lane, gc, beta); gL[lane] = gc; gL[64 + lane] = beta; const float eg = __expf(gc); gL[128 + lane] = eg; ((float*)(ex + 24576))[lane] = eg; }
;     __syncthreads();
;     const float gl = gL[63];
;     if (wid < 6) { const int part = wid % 3, th = wid / 3;
; DI void phase_gdn_pre(const Prm& p, unsigned char* lds, int tid, int wid, int lane) {
;     for (int u = blockIdx.x; u < NTB; u += gridDim.x) { int lv = lane, tv = tid; asm volatile("" : "+v"(lv), "+v"(tv)); gdn_pre_unit(p, lds, u, tv, wid, lv); }
.LBB0_1140:
	v_mov_b32_e32 v36, v212
	v_lshrrev_b32_e32 v100, 6, v212
	v_lshlrev_b32_e32 v100, 2, v100
	v_mov_b32_e32 v101, 0x74653210
	v_lshrrev_b32_e32 v100, v100, v101
	v_and_b32_e32 v100, 7, v100
	v_and_b32_e32 v101, 63, v212
	v_lshl_or_b32 v36, v100, 6, v101
	s_waitcnt vmcnt(0)
	s_barrier
	s_cmpk_gt_i32 s3, 0x88f
	v_readfirstlane_b32 s0, v36
	s_cbranch_scc1 .LBB0_1659
	s_ashr_i32 s2, s0, 6
	s_cmp_eq_u32 s2, 6
	s_cselect_b64 s[24:25], -1, 0
	s_cmp_lt_i32 s2, 6
	s_mul_hi_i32 s0, s2, 0x55555556
	s_cselect_b64 s[26:27], -1, 0
	s_lshr_b32 s1, s0, 31
	s_add_i32 s4, s0, s1
	s_mul_i32 s0, s4, 3
	v_writelane_b32 v246, s56, 16
	s_sub_i32 s5, s2, s0
	s_lshl_b32 s0, s5, 9
	v_writelane_b32 v246, s57, 17
	s_lshl_b32 s71, s4, 5
	v_writelane_b32 v246, s0, 18
	s_add_i32 s0, s71, -3
	s_cmp_lt_i32 s2, 3
	v_writelane_b32 v246, s0, 19
	s_cselect_b64 s[0:1], -1, 0
	v_writelane_b32 v246, s0, 20
	s_cmp_gt_i32 s2, 2
	s_cselect_b64 s[62:63], -1, 0
	v_writelane_b32 v246, s1, 21
	s_add_i32 s0, s71, -2
	v_writelane_b32 v246, s0, 22
	s_or_b32 s0, s71, 1
	v_writelane_b32 v246, s0, 23
	s_ashr_i32 s0, s0, 31
	v_writelane_b32 v246, s0, 24
	s_add_i32 s0, s71, -1
	v_writelane_b32 v246, s0, 25
	s_or_b32 s0, s71, 2
	s_ashr_i32 s87, s71, 31
	v_writelane_b32 v246, s0, 26
	s_ashr_i32 s0, s0, 31
	s_cmp_lg_u32 s5, 2
	s_cselect_b64 s[72:73], -1, 0
	s_cmp_lg_u32 s5, 0
	v_writelane_b32 v246, s0, 27
	s_mov_b32 s1, 0
	s_cselect_b64 s[54:55], -1, 0
	s_cmp_eq_u32 s5, 0
	v_writelane_b32 v246, s0, 28
	s_cselect_b64 s[64:65], -1, 0
	s_mov_b64 s[80:81], s[22:23]
	v_writelane_b32 v246, s1, 29
	s_and_b64 s[0:1], s[64:65], exec
	s_cselect_b32 s86, 0, 32
	s_cmp_eq_u32 s5, 2
	s_cselect_b32 s0, 32, 0
	v_writelane_b32 v246, s0, 30
	s_or_b32 s0, s86, 1
	v_writelane_b32 v246, s0, 31
	s_or_b32 s0, s86, 2
	v_writelane_b32 v246, s0, 32
	s_or_b32 s0, s86, 3
	v_writelane_b32 v246, s0, 33
	s_or_b32 s0, s86, 8
	v_writelane_b32 v246, s0, 34
	s_or_b32 s0, s86, 9
	v_writelane_b32 v246, s0, 35
	s_or_b32 s0, s86, 10
	v_writelane_b32 v246, s0, 36
	s_or_b32 s0, s86, 11
	v_writelane_b32 v246, s0, 37
	s_or_b32 s0, s86, 16
	v_writelane_b32 v246, s0, 38
	s_or_b32 s0, s86, 17
	v_writelane_b32 v246, s0, 39
	s_or_b32 s0, s86, 18
	v_writelane_b32 v246, s0, 40
	s_or_b32 s0, s86, 19
	v_writelane_b32 v246, s0, 41
	s_or_b32 s0, s86, 24
	v_writelane_b32 v246, s0, 42
	s_or_b32 s0, s86, 25
	v_writelane_b32 v246, s0, 43
	s_or_b32 s0, s86, 26
	v_writelane_b32 v246, s0, 44
	s_or_b32 s0, s86, 27
	s_cmp_lt_i32 s2, 4
	s_cselect_b64 s[82:83], -1, 0
	s_cmp_gt_i32 s2, 3
	v_writelane_b32 v246, s0, 45
	s_cselect_b64 s[76:77], -1, 0
	s_lshl_b32 s0, s2, 4
	v_writelane_b32 v246, s0, 46
	s_lshl_b32 s0, s2, 5
	s_and_b32 s59, s0, 0x60
	s_lshl_b32 s0, s2, 7
	s_add_u32 s75, s34, 0x1a61a800
	s_addc_u32 s33, s35, 0
	v_writelane_b32 v246, s0, 47
	s_add_u32 s0, s34, 0x1da07800
	v_writelane_b32 v246, s0, 48
	s_addc_u32 s0, s35, 0
	v_writelane_b32 v246, s0, 49
	s_add_u32 s0, s34, 0x1da03800
	v_writelane_b32 v246, s0, 50
	s_addc_u32 s0, s35, 0
	v_writelane_b32 v246, s0, 51
	s_add_u32 s0, s34, 0x1da0b800
	v_writelane_b32 v246, s0, 52
	s_addc_u32 s0, s35, 0
	v_writelane_b32 v246, s0, 53
	s_lshl_b32 s0, s4, 6
	s_add_i32 s0, s0, 0
	v_writelane_b32 v246, s0, 54
	s_mul_i32 s0, s4, 0x2200
	s_add_i32 s0, s0, 0
	v_writelane_b32 v246, s0, 55
	s_lshl_b32 s0, s4, 7
	s_add_i32 s0, s0, 0
	v_writelane_b32 v246, s0, 56
	s_mul_i32 s0, s4, 0x18000
	s_mul_hi_i32 s1, s71, 0xc00
	s_add_u32 s0, s34, s0
	v_readlane_b32 s8, v247, 11
	s_addc_u32 s1, s35, s1
	v_readlane_b32 s9, v247, 12
	v_readlane_b32 s10, v247, 13
	v_readlane_b32 s11, v247, 14
	v_readlane_b32 s12, v247, 15
	v_readlane_b32 s13, v247, 16
	v_readlane_b32 s14, v247, 17
	v_readlane_b32 s15, v247, 18
	s_add_u32 s0, s0, 0x1042fc00
	v_readlane_b32 s16, v247, 19
	v_readlane_b32 s17, v247, 20
	v_readlane_b32 s18, v247, 21
	v_readlane_b32 s19, v247, 22
	s_mov_b64 s[8:9], s[12:13]
	v_writelane_b32 v246, s0, 57
	s_addc_u32 s0, s1, 0
	s_mul_i32 s4, s4, 0x30000
	s_mov_b64 s[10:11], s[14:15]
	s_mov_b64 s[12:13], s[16:17]
	s_mov_b64 s[14:15], s[18:19]
	v_writelane_b32 v246, s0, 58
	s_mul_hi_i32 s0, s71, 0x1800
	s_add_u32 s1, s14, s4
	s_addc_u32 s0, s15, s0
	s_add_u32 s1, s1, 0xa800
	v_writelane_b32 v246, s1, 59
	s_addc_u32 s0, s0, 0
	v_readlane_b32 s20, v247, 23
	v_readlane_b32 s21, v247, 24
	v_writelane_b32 v246, s0, 60
	v_and_b32_e32 v37, 63, v36
	s_mov_b32 s78, 0x800000
	v_mov_b32_e32 v33, 0
	v_cndmask_b32_e64 v38, 0, 1, s[26:27]
	s_movk_i32 s20, 0x110
	s_movk_i32 s21, 0x90
	v_mov_b32_e32 v39, 0x41b17218
	v_mov_b32_e32 v40, 0x1600
	v_mov_b32_e32 v41, 0x1800
	v_mov_b32_e32 v42, 0xc00
	s_add_i32 s2, s3, 144
	s_and_b32 s2, s2, 0xff
	v_readlane_b32 s22, v247, 25
	v_readlane_b32 s23, v247, 26
	s_branch .LBB0_1144
